# sync fast paths: L1 invalidate issued with the first flag poll in split/quad/group waits (second invalidate dropped where the waiting CU issues no loads); plus cp address-math rewrite
# speedup vs baseline: 1.0246x; 1.0080x over previous
.LBB0_668:
	s_or_b64 exec, exec, s[10:11]
	v_mov_b32_e32 v1, 0
	global_load_dword v2, v1, s[8:9] sc1
	buffer_inv sc1
	s_waitcnt vmcnt(0)
	v_cmp_lt_u32_e32 vcc, 31, v2
	s_cbranch_vccnz .LBB0_682
	v_readlane_b32 s0, v246, 2
	v_readlane_b32 s1, v246, 3
	s_add_u32 s10, s0, 0x4200
	s_addc_u32 s11, s1, 0
	s_mov_b32 s0, 1
	s_branch .LBB0_671

.LBB0_681:
	s_waitcnt vmcnt(0)
	s_waitcnt vmcnt(0)

.LBB0_705:
	s_and_saveexec_b64 s[6:7], s[80:81]
	v_readlane_b32 s88, v246, 10
	v_readlane_b32 s86, v246, 7
	v_readlane_b32 s79, v246, 9
	v_readlane_b32 s89, v246, 11
	v_readlane_b32 s18, v246, 12
	v_readlane_b32 s87, v246, 8
	s_cbranch_execz .LBB0_720
	s_add_i32 s0, 0, 0x20164
	v_mov_b32_e32 v2, s0
	v_readlane_b32 s0, v246, 2
	v_mov_b32_e32 v3, 0x3000
	v_readlane_b32 s1, v246, 3
	ds_read_b32 v2, v2
	s_add_u32 s10, s0, 0x3300
	s_addc_u32 s11, s1, 0
	s_nop 1
	global_load_dword v3, v3, s[0:1] offset:768 sc1
	buffer_inv sc1
	s_waitcnt vmcnt(0) lgkmcnt(0)
	v_cmp_ge_u32_e32 vcc, v3, v2
	s_cbranch_vccnz .LBB0_720
	v_readlane_b32 s0, v246, 2
	v_readlane_b32 s1, v246, 3
	s_add_u32 s8, s0, 0x4200
	s_addc_u32 s9, s1, 0
	s_mov_b32 s0, 1
	v_mov_b32_e32 v3, 0
	s_branch .LBB0_709

.LBB0_742:
	s_or_b64 exec, exec, s[10:11]
	v_mov_b32_e32 v1, 0
	global_load_dword v2, v1, s[8:9] sc1
	buffer_inv sc1
	s_waitcnt vmcnt(0)
	v_cmp_lt_u32_e32 vcc, 63, v2
	s_cbranch_vccnz .LBB0_756
	v_readlane_b32 s0, v246, 2
	v_readlane_b32 s1, v246, 3
	s_add_u32 s10, s0, 0x4200
	s_addc_u32 s11, s1, 0
	s_mov_b32 s0, 1
	s_branch .LBB0_745

.LBB0_785:
	s_or_b64 exec, exec, s[2:3]
	s_cmp_lt_i32 s88, 5
	s_cselect_b64 s[0:1], -1, 0
	s_cmp_gt_i32 s89, 4
	s_cselect_b64 s[2:3], -1, 0
	s_and_b64 s[0:1], s[0:1], s[2:3]
	s_andn2_b64 vcc, exec, s[0:1]
	s_cbranch_vccnz .LBB0_869
	s_and_saveexec_b64 s[6:7], s[80:81]
	s_cbranch_execz .LBB0_815
	s_lshl_b32 s8, s33, 4
	s_ashr_i32 s9, s8, 31
	s_lshl_b64 s[0:1], s[8:9], 2
	v_readlane_b32 s2, v246, 2
	v_readlane_b32 s3, v246, 3
	s_add_u32 s0, s2, s0
	s_addc_u32 s1, s3, s1
	v_mov_b32_e32 v1, 0x1000
	global_load_dword v1, v1, s[0:1] sc1
	buffer_inv sc1
	s_add_u32 s12, s0, 0x1000
	s_addc_u32 s13, s1, 0
	s_waitcnt vmcnt(0)
	v_cmp_lt_u32_e32 vcc, 3, v1
	s_cbranch_vccnz .LBB0_800
	v_readlane_b32 s0, v246, 2
	v_readlane_b32 s1, v246, 3
	s_add_u32 s10, s0, 0x4200
	s_addc_u32 s11, s1, 0
	s_mov_b32 s0, 1
	v_mov_b32_e32 v1, 0
	s_branch .LBB0_790

.LBB0_849:
	s_or_b64 exec, exec, s[6:7]
	s_waitcnt lgkmcnt(0)
	s_barrier
	s_and_saveexec_b64 s[6:7], s[80:81]
	s_cbranch_execz .LBB0_864
	s_add_i32 s0, 0, 0x20164
	v_mov_b32_e32 v2, s0
	v_readlane_b32 s0, v246, 2
	v_mov_b32_e32 v3, 0x3000
	v_readlane_b32 s1, v246, 3
	ds_read_b32 v2, v2
	s_add_u32 s10, s0, 0x3340
	s_addc_u32 s11, s1, 0
	s_nop 1
	global_load_dword v3, v3, s[0:1] offset:832 sc1
	buffer_inv sc1
	s_waitcnt vmcnt(0) lgkmcnt(0)
	v_cmp_ge_u32_e32 vcc, v3, v2
	s_cbranch_vccnz .LBB0_864
	v_readlane_b32 s0, v246, 2
	v_readlane_b32 s1, v246, 3
	s_add_u32 s8, s0, 0x4200
	s_addc_u32 s9, s1, 0
	s_mov_b32 s0, 1
	v_mov_b32_e32 v3, 0
	s_branch .LBB0_853

.LBB0_869:
	s_cmp_lt_i32 s88, 7
	s_cselect_b64 s[0:1], -1, 0
	s_cmp_gt_i32 s89, 6
	s_cselect_b64 s[2:3], -1, 0
	s_and_b64 s[0:1], s[0:1], s[2:3]
	s_andn2_b64 vcc, exec, s[0:1]
	s_cbranch_vccnz .LBB0_947
	s_and_saveexec_b64 s[6:7], s[80:81]
	s_cbranch_execz .LBB0_897
	s_lshl_b32 s0, s33, 4
	s_ashr_i32 s1, s0, 31
	s_lshl_b64 s[0:1], s[0:1], 2
	v_readlane_b32 s2, v246, 2
	v_readlane_b32 s3, v246, 3
	s_add_u32 s0, s2, s0
	s_addc_u32 s1, s3, s1
	v_mov_b32_e32 v1, 0x1000
	global_load_dword v1, v1, s[0:1] sc1
	buffer_inv sc1
	s_add_u32 s10, s0, 0x1000
	s_addc_u32 s11, s1, 0
	s_waitcnt vmcnt(0)
	v_cmp_lt_u32_e32 vcc, 7, v1
	s_cbranch_vccnz .LBB0_897
	v_readlane_b32 s0, v246, 2
	v_readlane_b32 s1, v246, 3
	s_add_u32 s8, s0, 0x4200
	s_addc_u32 s9, s1, 0
	s_mov_b32 s0, 1
	v_mov_b32_e32 v1, 0
	s_branch .LBB0_874

.LBB0_925:
	s_waitcnt vmcnt(0)
	s_barrier
	s_and_saveexec_b64 s[6:7], s[80:81]
	s_cbranch_execz .LBB0_940
	s_add_i32 s0, 0, 0x20164
	v_mov_b32_e32 v2, s0
	v_readlane_b32 s0, v246, 2
	s_waitcnt lgkmcnt(0)
	v_mov_b32_e32 v3, 0x3000
	v_readlane_b32 s1, v246, 3
	ds_read_b32 v2, v2
	s_add_u32 s10, s0, 0x3240
	s_addc_u32 s11, s1, 0
	s_nop 1
	global_load_dword v3, v3, s[0:1] offset:576 sc1
	buffer_inv sc1
	s_waitcnt vmcnt(0) lgkmcnt(0)
	v_cmp_ge_u32_e32 vcc, v3, v2
	s_cbranch_vccnz .LBB0_940
	v_readlane_b32 s0, v246, 2
	v_readlane_b32 s1, v246, 3
	s_add_u32 s8, s0, 0x4200
	s_addc_u32 s9, s1, 0
	s_mov_b32 s0, 1
	v_mov_b32_e32 v3, 0
	s_branch .LBB0_929

.LBB0_947:
	s_cmp_lt_i32 s88, 8
	s_cselect_b64 s[0:1], -1, 0
	s_cmp_gt_i32 s89, 7
	s_cselect_b64 s[2:3], -1, 0
	s_and_b64 s[0:1], s[0:1], s[2:3]
	s_andn2_b64 vcc, exec, s[0:1]
	s_cbranch_vccnz .LBB0_1072
	s_and_saveexec_b64 s[6:7], s[80:81]
	s_cbranch_execz .LBB0_975
	s_lshl_b32 s0, s33, 4
	s_ashr_i32 s1, s0, 31
	s_lshl_b64 s[0:1], s[0:1], 2
	v_readlane_b32 s2, v246, 2
	v_readlane_b32 s3, v246, 3
	s_add_u32 s0, s2, s0
	s_addc_u32 s1, s3, s1
	v_mov_b32_e32 v1, 0x1000
	global_load_dword v1, v1, s[0:1] sc1
	buffer_inv sc1
	s_add_u32 s10, s0, 0x1000
	s_addc_u32 s11, s1, 0
	s_waitcnt vmcnt(0)
	v_cmp_lt_u32_e32 vcc, 11, v1
	s_cbranch_vccnz .LBB0_975
	v_readlane_b32 s0, v246, 2
	v_readlane_b32 s1, v246, 3
	s_add_u32 s8, s0, 0x4200
	s_addc_u32 s9, s1, 0
	s_mov_b32 s0, 1
	v_mov_b32_e32 v1, 0
	s_branch .LBB0_952

.LBB0_1040:
	s_waitcnt vmcnt(0)
	s_barrier
	s_and_saveexec_b64 s[6:7], s[80:81]
	s_cbranch_execz .LBB0_1055
	s_add_i32 s0, 0, 0x20164
	v_mov_b32_e32 v2, s0
	v_readlane_b32 s0, v246, 2
	v_mov_b32_e32 v3, 0x3000
	v_readlane_b32 s1, v246, 3
	ds_read_b32 v2, v2
	s_add_u32 s10, s0, 0x3280
	s_addc_u32 s11, s1, 0
	s_nop 1
	global_load_dword v3, v3, s[0:1] offset:640 sc1
	buffer_inv sc1
	s_waitcnt vmcnt(0) lgkmcnt(0)
	v_cmp_ge_u32_e32 vcc, v3, v2
	s_cbranch_vccnz .LBB0_1055
	v_readlane_b32 s0, v246, 2
	v_readlane_b32 s1, v246, 3
	s_add_u32 s8, s0, 0x4200
	s_addc_u32 s9, s1, 0
	s_mov_b32 s0, 1
	v_mov_b32_e32 v3, 0
	s_branch .LBB0_1044

.LBB0_1072:
	s_cmp_lt_i32 s88, 9
	s_cselect_b64 s[0:1], -1, 0
	s_cmp_gt_i32 s89, 8
	s_cselect_b64 s[2:3], -1, 0
	s_and_b64 s[0:1], s[0:1], s[2:3]
	s_andn2_b64 vcc, exec, s[0:1]
	s_cbranch_vccnz .LBB0_1130
	s_and_saveexec_b64 s[6:7], s[80:81]
	s_cbranch_execz .LBB0_1100
	s_lshl_b32 s0, s33, 4
	s_ashr_i32 s1, s0, 31
	s_lshl_b64 s[0:1], s[0:1], 2
	v_readlane_b32 s2, v246, 2
	v_readlane_b32 s3, v246, 3
	s_add_u32 s0, s2, s0
	s_addc_u32 s1, s3, s1
	v_mov_b32_e32 v1, 0x1000
	global_load_dword v1, v1, s[0:1] sc1
	buffer_inv sc1
	s_add_u32 s10, s0, 0x1000
	s_addc_u32 s11, s1, 0
	s_waitcnt vmcnt(0)
	v_cmp_lt_u32_e32 vcc, 15, v1
	s_cbranch_vccnz .LBB0_1100
	v_readlane_b32 s0, v246, 2
	v_readlane_b32 s1, v246, 3
	s_add_u32 s8, s0, 0x4200
	s_addc_u32 s9, s1, 0
	s_mov_b32 s0, 1
	v_mov_b32_e32 v1, 0
	s_branch .LBB0_1077

.LBB0_1114:
	s_waitcnt vmcnt(0)
	s_barrier
	s_and_saveexec_b64 s[6:7], s[80:81]
	s_cbranch_execz .LBB0_1129
	s_add_i32 s0, 0, 0x20164
	v_mov_b32_e32 v2, s0
	v_readlane_b32 s0, v246, 2
	v_mov_b32_e32 v3, 0x3000
	v_readlane_b32 s1, v246, 3
	ds_read_b32 v2, v2
	s_add_u32 s10, s0, 0x32c0
	s_addc_u32 s11, s1, 0
	s_nop 1
	global_load_dword v3, v3, s[0:1] offset:704 sc1
	buffer_inv sc1
	s_waitcnt vmcnt(0) lgkmcnt(0)
	v_cmp_ge_u32_e32 vcc, v3, v2
	s_cbranch_vccnz .LBB0_1129
	v_readlane_b32 s0, v246, 2
	v_readlane_b32 s1, v246, 3
	s_add_u32 s8, s0, 0x4200
	s_addc_u32 s9, s1, 0
	s_mov_b32 s0, 1
	v_mov_b32_e32 v3, 0
	s_branch .LBB0_1118
